# P6 fused epilogue pass 2 (H1 stores) through cross-wave LDS exchange so each store writes full contiguous 512B row segments, on top of P8 row-store
# speedup vs baseline: 1.0270x; 1.0109x over previous
.LBB0_1592:
	s_or_b64 exec, exec, s[48:49]
	s_waitcnt vmcnt(9)
	v_pk_add_f32 v[92:93], v[92:93], 1.0 op_sel_hi:[1,0]
	s_waitcnt lgkmcnt(0)
	v_pk_mul_f32 v[84:85], v[84:85], v[92:93]
	s_barrier
	v_and_b32_e32 v176, 15, v228
	v_lshrrev_b32_e32 v177, 6, v228
	v_lshrrev_b32_e32 v178, 3, v230
	v_and_b32_e32 v179, 7, v176
	v_xor_b32_e32 v179, v178, v179
	v_mul_u32_u24_e32 v180, 0x2400, v177
	v_add_u32_e32 v180, 0x20000, v180
	v_lshl_add_u32 v144, v176, 9, v180
	v_lshl_add_u32 v144, v179, 4, v144
	v_lshrrev_b32_e32 v181, 5, v230
	v_lshrrev_b32_e32 v182, 5, v236
	v_lshl_add_u32 v181, v181, 2, v182
	v_and_b32_e32 v182, 31, v236
	v_and_b32_e32 v183, 7, v181
	v_xor_b32_e32 v183, v182, v183
	v_lshl_add_u32 v145, v181, 9, v180
	v_lshl_add_u32 v145, v183, 4, v145
	v_add_u32_e32 v183, 2, v181
	v_lshl_add_u32 v146, v183, 9, v180
	v_and_b32_e32 v183, 7, v183
	v_xor_b32_e32 v183, v182, v183
	v_lshl_add_u32 v146, v183, 4, v146
	v_sub_u32_e32 v183, v181, v176
	v_lshlrev_b32_e32 v183, 11, v183
	v_lshlrev_b32_e32 v182, 3, v182
	v_sub_u32_e32 v182, v182, v230
	v_lshl_add_u32 v148, v182, 1, v183
	v_ashrrev_i32_e32 v149, 31, v148
	s_mov_b64 s[98:99], 0x1000
	ds_read_b32 v92, v232
	s_waitcnt vmcnt(8)
	v_pk_add_f32 v[90:91], v[90:91], 1.0 op_sel_hi:[1,0]
	v_pk_add_f32 v[88:89], v[88:89], 1.0 op_sel_hi:[1,0]
	v_pk_add_f32 v[94:95], v[94:95], 1.0 op_sel_hi:[1,0]
	v_pk_mul_f32 v[82:83], v[82:83], v[90:91]
	v_pk_mul_f32 v[80:81], v[80:81], v[88:89]
	v_lshlrev_b32_e32 v88, 16, v8
	v_and_b32_e32 v89, 0xffff0000, v8
	v_lshlrev_b32_e32 v8, 16, v9
	v_and_b32_e32 v9, 0xffff0000, v9
	v_lshlrev_b32_e32 v90, 16, v10
	v_and_b32_e32 v91, 0xffff0000, v10
	v_lshlrev_b32_e32 v10, 16, v11
	v_and_b32_e32 v11, 0xffff0000, v11
	v_pk_mul_f32 v[86:87], v[86:87], v[94:95]
	s_waitcnt lgkmcnt(0)
	v_pk_mul_f32 v[88:89], v[92:93], v[88:89] op_sel_hi:[0,1]
	v_pk_mul_f32 v[8:9], v[92:93], v[8:9] op_sel_hi:[0,1]
	v_pk_mul_f32 v[90:91], v[92:93], v[90:91] op_sel_hi:[0,1]
	v_pk_mul_f32 v[10:11], v[92:93], v[10:11] op_sel_hi:[0,1]
	s_waitcnt vmcnt(6)
	v_pk_fma_f32 v[8:9], v[82:83], v[8:9], v[78:79]
	v_pk_fma_f32 v[88:89], v[80:81], v[88:89], v[76:77]
	v_pk_fma_f32 v[10:11], v[86:87], v[10:11], v[74:75]
	v_pk_fma_f32 v[90:91], v[84:85], v[90:91], v[72:73]
	v_cvt_pk_bf16_f32 v88, v88, v89
	v_cvt_pk_bf16_f32 v89, v8, v9
	v_lshlrev_b64 v[8:9], 1, v[208:209]
	v_cvt_pk_bf16_f32 v90, v90, v91
	v_cvt_pk_bf16_f32 v91, v10, v11
	v_lshl_add_u64 v[10:11], s[10:11], 0, v[212:213]
	v_lshl_add_u64 v[10:11], v[10:11], 0, v[8:9]
	s_waitcnt vmcnt(2)
	v_pk_add_f32 v[106:107], v[106:107], 1.0 op_sel_hi:[1,0]
	v_pk_add_f32 v[104:105], v[104:105], 1.0 op_sel_hi:[1,0]
	ds_write_b128 v144, v[88:91]
	v_pk_add_f32 v[110:111], v[110:111], 1.0 op_sel_hi:[1,0]
	v_pk_add_f32 v[108:109], v[108:109], 1.0 op_sel_hi:[1,0]
	v_lshlrev_b32_e32 v88, 16, v4
	v_and_b32_e32 v89, 0xffff0000, v4
	v_lshlrev_b32_e32 v4, 16, v5
	v_and_b32_e32 v5, 0xffff0000, v5
	v_pk_mul_f32 v[98:99], v[98:99], v[106:107]
	v_pk_mul_f32 v[96:97], v[96:97], v[104:105]
	v_lshlrev_b32_e32 v90, 16, v6
	v_and_b32_e32 v91, 0xffff0000, v6
	v_lshlrev_b32_e32 v6, 16, v7
	v_and_b32_e32 v7, 0xffff0000, v7
	v_pk_mul_f32 v[88:89], v[92:93], v[88:89] op_sel_hi:[0,1]
	v_pk_mul_f32 v[4:5], v[92:93], v[4:5] op_sel_hi:[0,1]
	v_pk_mul_f32 v[100:101], v[100:101], v[108:109]
	v_pk_mul_f32 v[102:103], v[102:103], v[110:111]
	s_waitcnt vmcnt(0)
	v_pk_fma_f32 v[94:95], v[98:99], v[4:5], v[66:67]
	v_pk_fma_f32 v[4:5], v[96:97], v[88:89], v[64:65]
	v_pk_mul_f32 v[88:89], v[92:93], v[90:91] op_sel_hi:[0,1]
	v_pk_mul_f32 v[6:7], v[92:93], v[6:7] op_sel_hi:[0,1]
	v_pk_fma_f32 v[90:91], v[102:103], v[6:7], v[42:43]
	v_pk_fma_f32 v[6:7], v[100:101], v[88:89], v[40:41]
	v_cvt_pk_bf16_f32 v4, v4, v5
	v_cvt_pk_bf16_f32 v5, v94, v95
	s_andn2_b64 vcc, exec, s[4:5]
	v_cvt_pk_bf16_f32 v6, v6, v7
	v_cvt_pk_bf16_f32 v7, v90, v91
	ds_write_b128 v144, v[4:7] offset:256
	v_lshl_add_u64 v[150:151], v[10:11], 0, v[148:149]
	s_waitcnt lgkmcnt(0)
	s_barrier
	ds_read_b128 v[168:171], v145
	ds_read_b128 v[172:175], v146
	v_lshl_add_u64 v[152:153], v[150:151], 0, s[98:99]
	s_waitcnt lgkmcnt(0)
	s_barrier
	global_store_dwordx4 v[150:151], v[168:171], off
	global_store_dwordx4 v[152:153], v[172:175], off
	ds_read_b32 v4, v232 offset:64
	v_lshlrev_b32_e32 v10, 16, v2
	v_lshlrev_b32_e32 v6, 16, v0
	v_and_b32_e32 v7, 0xffff0000, v0
	v_lshlrev_b32_e32 v0, 16, v1
	v_and_b32_e32 v1, 0xffff0000, v1
	v_and_b32_e32 v11, 0xffff0000, v2
	v_lshlrev_b32_e32 v2, 16, v3
	v_and_b32_e32 v3, 0xffff0000, v3
	s_waitcnt lgkmcnt(0)
	v_pk_mul_f32 v[6:7], v[4:5], v[6:7] op_sel_hi:[0,1]
	v_pk_mul_f32 v[0:1], v[4:5], v[0:1] op_sel_hi:[0,1]
	v_pk_fma_f32 v[88:89], v[82:83], v[0:1], v[78:79]
	v_pk_fma_f32 v[0:1], v[80:81], v[6:7], v[76:77]
	v_pk_mul_f32 v[6:7], v[4:5], v[10:11] op_sel_hi:[0,1]
	v_pk_mul_f32 v[2:3], v[4:5], v[2:3] op_sel_hi:[0,1]
	v_pk_fma_f32 v[10:11], v[86:87], v[2:3], v[74:75]
	v_pk_fma_f32 v[2:3], v[84:85], v[6:7], v[72:73]
	v_lshl_add_u64 v[6:7], s[10:11], 0, v[210:211]
	v_cvt_pk_bf16_f32 v0, v0, v1
	v_cvt_pk_bf16_f32 v1, v88, v89
	v_cvt_pk_bf16_f32 v2, v2, v3
	v_cvt_pk_bf16_f32 v3, v10, v11
	v_lshl_add_u64 v[6:7], v[6:7], 0, v[8:9]
	ds_write_b128 v144, v[0:3]
	v_lshlrev_b32_e32 v10, 16, v14
	v_and_b32_e32 v11, 0xffff0000, v14
	v_lshlrev_b32_e32 v0, 16, v12
	v_and_b32_e32 v1, 0xffff0000, v12
	v_lshlrev_b32_e32 v2, 16, v13
	v_and_b32_e32 v3, 0xffff0000, v13
	v_lshlrev_b32_e32 v12, 16, v15
	v_and_b32_e32 v13, 0xffff0000, v15
	v_pk_mul_f32 v[0:1], v[4:5], v[0:1] op_sel_hi:[0,1]
	v_pk_mul_f32 v[2:3], v[4:5], v[2:3] op_sel_hi:[0,1]
	v_pk_mul_f32 v[10:11], v[4:5], v[10:11] op_sel_hi:[0,1]
	v_pk_mul_f32 v[4:5], v[4:5], v[12:13] op_sel_hi:[0,1]
	v_pk_fma_f32 v[2:3], v[98:99], v[2:3], v[66:67]
	v_pk_fma_f32 v[0:1], v[96:97], v[0:1], v[64:65]
	v_pk_fma_f32 v[4:5], v[102:103], v[4:5], v[42:43]
	v_pk_fma_f32 v[10:11], v[100:101], v[10:11], v[40:41]
	v_cvt_pk_bf16_f32 v0, v0, v1
	v_cvt_pk_bf16_f32 v1, v2, v3
	v_lshlrev_b32_e32 v12, 16, v27
	v_cvt_pk_bf16_f32 v2, v10, v11
	v_cvt_pk_bf16_f32 v3, v4, v5
	ds_read_b32 v4, v232 offset:128
	ds_write_b128 v144, v[0:3] offset:256
	v_lshl_add_u64 v[150:151], v[6:7], 0, v[148:149]
	s_waitcnt lgkmcnt(0)
	s_barrier
	ds_read_b128 v[168:171], v145
	ds_read_b128 v[172:175], v146
	v_lshl_add_u64 v[152:153], v[150:151], 0, s[98:99]
	s_waitcnt lgkmcnt(0)
	s_barrier
	global_store_dwordx4 v[150:151], v[168:171], off
	global_store_dwordx4 v[152:153], v[172:175], off
	v_lshlrev_b32_e32 v6, 16, v18
	v_and_b32_e32 v7, 0xffff0000, v18
	v_lshlrev_b32_e32 v0, 16, v16
	v_and_b32_e32 v1, 0xffff0000, v16
	v_lshlrev_b32_e32 v2, 16, v17
	v_and_b32_e32 v3, 0xffff0000, v17
	s_waitcnt lgkmcnt(0)
	v_pk_mul_f32 v[0:1], v[4:5], v[0:1] op_sel_hi:[0,1]
	v_pk_mul_f32 v[2:3], v[4:5], v[2:3] op_sel_hi:[0,1]
	v_pk_mul_f32 v[6:7], v[4:5], v[6:7] op_sel_hi:[0,1]
	v_lshlrev_b32_e32 v10, 16, v19
	v_and_b32_e32 v11, 0xffff0000, v19
	v_pk_fma_f32 v[2:3], v[82:83], v[2:3], v[78:79]
	v_pk_fma_f32 v[0:1], v[80:81], v[0:1], v[76:77]
	v_pk_fma_f32 v[6:7], v[84:85], v[6:7], v[72:73]
	v_pk_mul_f32 v[10:11], v[4:5], v[10:11] op_sel_hi:[0,1]
	v_cvt_pk_bf16_f32 v0, v0, v1
	v_cvt_pk_bf16_f32 v1, v2, v3
	v_cvt_pk_bf16_f32 v2, v6, v7
	v_lshl_add_u64 v[6:7], s[10:11], 0, v[214:215]
	v_pk_fma_f32 v[10:11], v[86:87], v[10:11], v[74:75]
	v_lshl_add_u64 v[6:7], v[6:7], 0, v[8:9]
	v_cvt_pk_bf16_f32 v3, v10, v11
	ds_write_b128 v144, v[0:3]
	v_lshlrev_b32_e32 v10, 16, v26
	v_and_b32_e32 v11, 0xffff0000, v26
	v_lshlrev_b32_e32 v0, 16, v24
	v_and_b32_e32 v1, 0xffff0000, v24
	v_lshlrev_b32_e32 v2, 16, v25
	v_and_b32_e32 v3, 0xffff0000, v25
	v_and_b32_e32 v13, 0xffff0000, v27
	v_pk_mul_f32 v[0:1], v[4:5], v[0:1] op_sel_hi:[0,1]
	v_pk_mul_f32 v[2:3], v[4:5], v[2:3] op_sel_hi:[0,1]
	v_pk_mul_f32 v[10:11], v[4:5], v[10:11] op_sel_hi:[0,1]
	v_pk_mul_f32 v[4:5], v[4:5], v[12:13] op_sel_hi:[0,1]
	v_pk_fma_f32 v[2:3], v[98:99], v[2:3], v[66:67]
	v_pk_fma_f32 v[0:1], v[96:97], v[0:1], v[64:65]
	v_pk_fma_f32 v[4:5], v[102:103], v[4:5], v[42:43]
	v_pk_fma_f32 v[10:11], v[100:101], v[10:11], v[40:41]
	v_cvt_pk_bf16_f32 v0, v0, v1
	v_cvt_pk_bf16_f32 v1, v2, v3
	v_lshlrev_b32_e32 v12, 16, v31
	v_cvt_pk_bf16_f32 v2, v10, v11
	v_cvt_pk_bf16_f32 v3, v4, v5
	ds_read_b32 v4, v232 offset:192
	ds_write_b128 v144, v[0:3] offset:256
	v_lshl_add_u64 v[150:151], v[6:7], 0, v[148:149]
	s_waitcnt lgkmcnt(0)
	s_barrier
	ds_read_b128 v[168:171], v145
	ds_read_b128 v[172:175], v146
	v_lshl_add_u64 v[152:153], v[150:151], 0, s[98:99]
	s_waitcnt lgkmcnt(0)
	s_barrier
	global_store_dwordx4 v[150:151], v[168:171], off
	global_store_dwordx4 v[152:153], v[172:175], off
	v_lshlrev_b32_e32 v6, 16, v22
	v_and_b32_e32 v7, 0xffff0000, v22
	v_lshlrev_b32_e32 v0, 16, v20
	v_and_b32_e32 v1, 0xffff0000, v20
	v_lshlrev_b32_e32 v2, 16, v21
	v_and_b32_e32 v3, 0xffff0000, v21
	s_waitcnt lgkmcnt(0)
	v_pk_mul_f32 v[0:1], v[4:5], v[0:1] op_sel_hi:[0,1]
	v_pk_mul_f32 v[2:3], v[4:5], v[2:3] op_sel_hi:[0,1]
	v_pk_mul_f32 v[6:7], v[4:5], v[6:7] op_sel_hi:[0,1]
	v_lshlrev_b32_e32 v10, 16, v23
	v_and_b32_e32 v11, 0xffff0000, v23
	v_pk_fma_f32 v[2:3], v[82:83], v[2:3], v[78:79]
	v_pk_fma_f32 v[0:1], v[80:81], v[0:1], v[76:77]
	v_pk_fma_f32 v[6:7], v[84:85], v[6:7], v[72:73]
	v_pk_mul_f32 v[10:11], v[4:5], v[10:11] op_sel_hi:[0,1]
	v_cvt_pk_bf16_f32 v0, v0, v1
	v_cvt_pk_bf16_f32 v1, v2, v3
	v_cvt_pk_bf16_f32 v2, v6, v7
	v_lshl_add_u64 v[6:7], s[10:11], 0, v[160:161]
	v_pk_fma_f32 v[10:11], v[86:87], v[10:11], v[74:75]
	v_lshl_add_u64 v[6:7], v[6:7], 0, v[8:9]
	v_cvt_pk_bf16_f32 v3, v10, v11
	ds_write_b128 v144, v[0:3]
	v_lshlrev_b32_e32 v10, 16, v30
	v_and_b32_e32 v11, 0xffff0000, v30
	v_lshlrev_b32_e32 v0, 16, v28
	v_and_b32_e32 v1, 0xffff0000, v28
	v_lshlrev_b32_e32 v2, 16, v29
	v_and_b32_e32 v3, 0xffff0000, v29
	v_and_b32_e32 v13, 0xffff0000, v31
	v_pk_mul_f32 v[0:1], v[4:5], v[0:1] op_sel_hi:[0,1]
	v_pk_mul_f32 v[2:3], v[4:5], v[2:3] op_sel_hi:[0,1]
	v_pk_mul_f32 v[10:11], v[4:5], v[10:11] op_sel_hi:[0,1]
	v_pk_mul_f32 v[4:5], v[4:5], v[12:13] op_sel_hi:[0,1]
	v_pk_fma_f32 v[2:3], v[98:99], v[2:3], v[66:67]
	v_pk_fma_f32 v[0:1], v[96:97], v[0:1], v[64:65]
	v_pk_fma_f32 v[4:5], v[102:103], v[4:5], v[42:43]
	v_pk_fma_f32 v[10:11], v[100:101], v[10:11], v[40:41]
	v_cvt_pk_bf16_f32 v0, v0, v1
	v_cvt_pk_bf16_f32 v1, v2, v3
	v_lshlrev_b32_e32 v12, 16, v51
	v_cvt_pk_bf16_f32 v2, v10, v11
	v_cvt_pk_bf16_f32 v3, v4, v5
	ds_read_b32 v4, v232 offset:512
	ds_write_b128 v144, v[0:3] offset:256
	v_lshl_add_u64 v[150:151], v[6:7], 0, v[148:149]
	s_waitcnt lgkmcnt(0)
	s_barrier
	ds_read_b128 v[168:171], v145
	ds_read_b128 v[172:175], v146
	v_lshl_add_u64 v[152:153], v[150:151], 0, s[98:99]
	s_waitcnt lgkmcnt(0)
	s_barrier
	global_store_dwordx4 v[150:151], v[168:171], off
	global_store_dwordx4 v[152:153], v[172:175], off
	v_lshlrev_b32_e32 v6, 16, v34
	v_and_b32_e32 v7, 0xffff0000, v34
	v_lshlrev_b32_e32 v0, 16, v32
	v_and_b32_e32 v1, 0xffff0000, v32
	v_lshlrev_b32_e32 v2, 16, v33
	v_and_b32_e32 v3, 0xffff0000, v33
	s_waitcnt lgkmcnt(0)
	v_pk_mul_f32 v[0:1], v[4:5], v[0:1] op_sel_hi:[0,1]
	v_pk_mul_f32 v[2:3], v[4:5], v[2:3] op_sel_hi:[0,1]
	v_pk_mul_f32 v[6:7], v[4:5], v[6:7] op_sel_hi:[0,1]
	v_lshlrev_b32_e32 v10, 16, v35
	v_and_b32_e32 v11, 0xffff0000, v35
	v_pk_fma_f32 v[2:3], v[82:83], v[2:3], v[78:79]
	v_pk_fma_f32 v[0:1], v[80:81], v[0:1], v[76:77]
	v_pk_fma_f32 v[6:7], v[84:85], v[6:7], v[72:73]
	v_pk_mul_f32 v[10:11], v[4:5], v[10:11] op_sel_hi:[0,1]
	v_cvt_pk_bf16_f32 v0, v0, v1
	v_cvt_pk_bf16_f32 v1, v2, v3
	v_cvt_pk_bf16_f32 v2, v6, v7
	v_lshl_add_u64 v[6:7], s[10:11], 0, v[162:163]
	v_pk_fma_f32 v[10:11], v[86:87], v[10:11], v[74:75]
	v_lshl_add_u64 v[6:7], v[6:7], 0, v[8:9]
	v_cvt_pk_bf16_f32 v3, v10, v11
	ds_write_b128 v144, v[0:3]
	v_lshlrev_b32_e32 v10, 16, v50
	v_and_b32_e32 v11, 0xffff0000, v50
	v_lshlrev_b32_e32 v0, 16, v48
	v_and_b32_e32 v1, 0xffff0000, v48
	v_lshlrev_b32_e32 v2, 16, v49
	v_and_b32_e32 v3, 0xffff0000, v49
	v_and_b32_e32 v13, 0xffff0000, v51
	v_pk_mul_f32 v[0:1], v[4:5], v[0:1] op_sel_hi:[0,1]
	v_pk_mul_f32 v[2:3], v[4:5], v[2:3] op_sel_hi:[0,1]
	v_pk_mul_f32 v[10:11], v[4:5], v[10:11] op_sel_hi:[0,1]
	v_pk_mul_f32 v[4:5], v[4:5], v[12:13] op_sel_hi:[0,1]
	v_pk_fma_f32 v[2:3], v[98:99], v[2:3], v[66:67]
	v_pk_fma_f32 v[0:1], v[96:97], v[0:1], v[64:65]
	v_pk_fma_f32 v[4:5], v[102:103], v[4:5], v[42:43]
	v_pk_fma_f32 v[10:11], v[100:101], v[10:11], v[40:41]
	v_cvt_pk_bf16_f32 v0, v0, v1
	v_cvt_pk_bf16_f32 v1, v2, v3
	v_lshlrev_b32_e32 v12, 16, v55
	v_cvt_pk_bf16_f32 v2, v10, v11
	v_cvt_pk_bf16_f32 v3, v4, v5
	ds_read_b32 v4, v232 offset:576
	ds_write_b128 v144, v[0:3] offset:256
	v_lshl_add_u64 v[150:151], v[6:7], 0, v[148:149]
	s_waitcnt lgkmcnt(0)
	s_barrier
	ds_read_b128 v[168:171], v145
	ds_read_b128 v[172:175], v146
	v_lshl_add_u64 v[152:153], v[150:151], 0, s[98:99]
	s_waitcnt lgkmcnt(0)
	s_barrier
	global_store_dwordx4 v[150:151], v[168:171], off
	global_store_dwordx4 v[152:153], v[172:175], off
	v_lshlrev_b32_e32 v6, 16, v46
	v_and_b32_e32 v7, 0xffff0000, v46
	v_lshlrev_b32_e32 v0, 16, v44
	v_and_b32_e32 v1, 0xffff0000, v44
	v_lshlrev_b32_e32 v2, 16, v45
	v_and_b32_e32 v3, 0xffff0000, v45
	s_waitcnt lgkmcnt(0)
	v_pk_mul_f32 v[0:1], v[4:5], v[0:1] op_sel_hi:[0,1]
	v_pk_mul_f32 v[2:3], v[4:5], v[2:3] op_sel_hi:[0,1]
	v_pk_mul_f32 v[6:7], v[4:5], v[6:7] op_sel_hi:[0,1]
	v_lshlrev_b32_e32 v10, 16, v47
	v_and_b32_e32 v11, 0xffff0000, v47
	v_pk_fma_f32 v[2:3], v[82:83], v[2:3], v[78:79]
	v_pk_fma_f32 v[0:1], v[80:81], v[0:1], v[76:77]
	v_pk_fma_f32 v[6:7], v[84:85], v[6:7], v[72:73]
	v_pk_mul_f32 v[10:11], v[4:5], v[10:11] op_sel_hi:[0,1]
	v_cvt_pk_bf16_f32 v0, v0, v1
	v_cvt_pk_bf16_f32 v1, v2, v3
	v_cvt_pk_bf16_f32 v2, v6, v7
	v_lshl_add_u64 v[6:7], s[10:11], 0, v[164:165]
	v_pk_fma_f32 v[10:11], v[86:87], v[10:11], v[74:75]
	v_lshl_add_u64 v[6:7], v[6:7], 0, v[8:9]
	v_cvt_pk_bf16_f32 v3, v10, v11
	ds_write_b128 v144, v[0:3]
	v_lshlrev_b32_e32 v10, 16, v54
	v_and_b32_e32 v11, 0xffff0000, v54
	v_lshlrev_b32_e32 v0, 16, v52
	v_and_b32_e32 v1, 0xffff0000, v52
	v_lshlrev_b32_e32 v2, 16, v53
	v_and_b32_e32 v3, 0xffff0000, v53
	v_and_b32_e32 v13, 0xffff0000, v55
	v_pk_mul_f32 v[0:1], v[4:5], v[0:1] op_sel_hi:[0,1]
	v_pk_mul_f32 v[2:3], v[4:5], v[2:3] op_sel_hi:[0,1]
	v_pk_mul_f32 v[10:11], v[4:5], v[10:11] op_sel_hi:[0,1]
	v_pk_mul_f32 v[4:5], v[4:5], v[12:13] op_sel_hi:[0,1]
	v_pk_fma_f32 v[2:3], v[98:99], v[2:3], v[66:67]
	v_pk_fma_f32 v[0:1], v[96:97], v[0:1], v[64:65]
	v_pk_fma_f32 v[4:5], v[102:103], v[4:5], v[42:43]
	v_pk_fma_f32 v[10:11], v[100:101], v[10:11], v[40:41]
	v_cvt_pk_bf16_f32 v0, v0, v1
	v_cvt_pk_bf16_f32 v1, v2, v3
	v_lshlrev_b32_e32 v12, 16, v71
	v_cvt_pk_bf16_f32 v2, v10, v11
	v_cvt_pk_bf16_f32 v3, v4, v5
	ds_read_b32 v4, v232 offset:640
	ds_write_b128 v144, v[0:3] offset:256
	v_lshl_add_u64 v[150:151], v[6:7], 0, v[148:149]
	s_waitcnt lgkmcnt(0)
	s_barrier
	ds_read_b128 v[168:171], v145
	ds_read_b128 v[172:175], v146
	v_lshl_add_u64 v[152:153], v[150:151], 0, s[98:99]
	s_waitcnt lgkmcnt(0)
	s_barrier
	global_store_dwordx4 v[150:151], v[168:171], off
	global_store_dwordx4 v[152:153], v[172:175], off
	v_lshlrev_b32_e32 v6, 16, v58
	v_and_b32_e32 v7, 0xffff0000, v58
	v_lshlrev_b32_e32 v0, 16, v56
	v_and_b32_e32 v1, 0xffff0000, v56
	v_lshlrev_b32_e32 v2, 16, v57
	v_and_b32_e32 v3, 0xffff0000, v57
	s_waitcnt lgkmcnt(0)
	v_pk_mul_f32 v[0:1], v[4:5], v[0:1] op_sel_hi:[0,1]
	v_pk_mul_f32 v[2:3], v[4:5], v[2:3] op_sel_hi:[0,1]
	v_pk_mul_f32 v[6:7], v[4:5], v[6:7] op_sel_hi:[0,1]
	v_lshlrev_b32_e32 v10, 16, v59
	v_and_b32_e32 v11, 0xffff0000, v59
	v_pk_fma_f32 v[2:3], v[82:83], v[2:3], v[78:79]
	v_pk_fma_f32 v[0:1], v[80:81], v[0:1], v[76:77]
	v_pk_fma_f32 v[6:7], v[84:85], v[6:7], v[72:73]
	v_pk_mul_f32 v[10:11], v[4:5], v[10:11] op_sel_hi:[0,1]
	v_cvt_pk_bf16_f32 v0, v0, v1
	v_cvt_pk_bf16_f32 v1, v2, v3
	v_cvt_pk_bf16_f32 v2, v6, v7
	v_lshl_add_u64 v[6:7], s[10:11], 0, v[120:121]
	v_pk_fma_f32 v[10:11], v[86:87], v[10:11], v[74:75]
	v_lshl_add_u64 v[6:7], v[6:7], 0, v[8:9]
	v_cvt_pk_bf16_f32 v3, v10, v11
	ds_write_b128 v144, v[0:3]
	v_lshlrev_b32_e32 v10, 16, v70
	v_and_b32_e32 v11, 0xffff0000, v70
	v_lshlrev_b32_e32 v0, 16, v68
	v_and_b32_e32 v1, 0xffff0000, v68
	v_lshlrev_b32_e32 v2, 16, v69
	v_and_b32_e32 v3, 0xffff0000, v69
	v_and_b32_e32 v13, 0xffff0000, v71
	v_pk_mul_f32 v[0:1], v[4:5], v[0:1] op_sel_hi:[0,1]
	v_pk_mul_f32 v[2:3], v[4:5], v[2:3] op_sel_hi:[0,1]
	v_pk_mul_f32 v[10:11], v[4:5], v[10:11] op_sel_hi:[0,1]
	v_pk_mul_f32 v[4:5], v[4:5], v[12:13] op_sel_hi:[0,1]
	v_pk_fma_f32 v[2:3], v[98:99], v[2:3], v[66:67]
	v_pk_fma_f32 v[0:1], v[96:97], v[0:1], v[64:65]
	v_pk_fma_f32 v[4:5], v[102:103], v[4:5], v[42:43]
	v_pk_fma_f32 v[10:11], v[100:101], v[10:11], v[40:41]
	v_cvt_pk_bf16_f32 v0, v0, v1
	v_cvt_pk_bf16_f32 v1, v2, v3
	s_mov_b64 s[4:5], -1
	v_cvt_pk_bf16_f32 v2, v10, v11
	v_cvt_pk_bf16_f32 v3, v4, v5
	ds_read_b32 v4, v232 offset:704
	ds_write_b128 v144, v[0:3] offset:256
	v_lshl_add_u64 v[150:151], v[6:7], 0, v[148:149]
	s_waitcnt lgkmcnt(0)
	s_barrier
	ds_read_b128 v[168:171], v145
	ds_read_b128 v[172:175], v146
	v_lshl_add_u64 v[152:153], v[150:151], 0, s[98:99]
	s_waitcnt lgkmcnt(0)
	s_barrier
	global_store_dwordx4 v[150:151], v[168:171], off
	global_store_dwordx4 v[152:153], v[172:175], off
	v_lshlrev_b32_e32 v6, 16, v62
	v_and_b32_e32 v7, 0xffff0000, v62
	v_lshlrev_b32_e32 v0, 16, v60
	v_and_b32_e32 v1, 0xffff0000, v60
	v_lshlrev_b32_e32 v2, 16, v61
	v_and_b32_e32 v3, 0xffff0000, v61
	s_waitcnt lgkmcnt(0)
	v_pk_mul_f32 v[0:1], v[4:5], v[0:1] op_sel_hi:[0,1]
	v_pk_mul_f32 v[2:3], v[4:5], v[2:3] op_sel_hi:[0,1]
	v_pk_mul_f32 v[6:7], v[4:5], v[6:7] op_sel_hi:[0,1]
	v_lshlrev_b32_e32 v10, 16, v63
	v_and_b32_e32 v11, 0xffff0000, v63
	v_pk_fma_f32 v[2:3], v[82:83], v[2:3], v[78:79]
	v_pk_fma_f32 v[0:1], v[80:81], v[0:1], v[76:77]
	v_pk_fma_f32 v[6:7], v[84:85], v[6:7], v[72:73]
	v_pk_mul_f32 v[10:11], v[4:5], v[10:11] op_sel_hi:[0,1]
	v_cvt_pk_bf16_f32 v0, v0, v1
	v_cvt_pk_bf16_f32 v1, v2, v3
	v_cvt_pk_bf16_f32 v2, v6, v7
	v_lshl_add_u64 v[6:7], s[10:11], 0, v[122:123]
	v_pk_fma_f32 v[10:11], v[86:87], v[10:11], v[74:75]
	v_lshl_add_u64 v[6:7], v[6:7], 0, v[8:9]
	v_cvt_pk_bf16_f32 v3, v10, v11
	ds_write_b128 v144, v[0:3]
	v_lshlrev_b32_e32 v8, 16, v38
	v_and_b32_e32 v9, 0xffff0000, v38
	v_lshlrev_b32_e32 v0, 16, v36
	v_and_b32_e32 v1, 0xffff0000, v36
	v_lshlrev_b32_e32 v2, 16, v37
	v_and_b32_e32 v3, 0xffff0000, v37
	v_lshlrev_b32_e32 v10, 16, v39
	v_and_b32_e32 v11, 0xffff0000, v39
	v_pk_mul_f32 v[0:1], v[4:5], v[0:1] op_sel_hi:[0,1]
	v_pk_mul_f32 v[2:3], v[4:5], v[2:3] op_sel_hi:[0,1]
	v_pk_fma_f32 v[2:3], v[98:99], v[2:3], v[66:67]
	v_pk_fma_f32 v[0:1], v[96:97], v[0:1], v[64:65]
	v_pk_mul_f32 v[8:9], v[4:5], v[8:9] op_sel_hi:[0,1]
	v_pk_mul_f32 v[4:5], v[4:5], v[10:11] op_sel_hi:[0,1]
	v_pk_fma_f32 v[4:5], v[102:103], v[4:5], v[42:43]
	v_pk_fma_f32 v[8:9], v[100:101], v[8:9], v[40:41]
	v_cvt_pk_bf16_f32 v0, v0, v1
	v_cvt_pk_bf16_f32 v1, v2, v3
	s_nop 0
	v_cvt_pk_bf16_f32 v2, v8, v9
	v_cvt_pk_bf16_f32 v3, v4, v5
	ds_write_b128 v144, v[0:3] offset:256
	v_lshl_add_u64 v[150:151], v[6:7], 0, v[148:149]
	s_waitcnt lgkmcnt(0)
	s_barrier
	ds_read_b128 v[168:171], v145
	ds_read_b128 v[172:175], v146
	v_lshl_add_u64 v[152:153], v[150:151], 0, s[98:99]
	s_waitcnt lgkmcnt(0)
	s_barrier
	global_store_dwordx4 v[150:151], v[168:171], off
	global_store_dwordx4 v[152:153], v[172:175], off
	s_cbranch_vccnz .LBB0_1471
	s_andn2_b64 vcc, exec, s[8:9]
	s_cbranch_vccnz .LBB0_1470
	s_barrier
	s_branch .LBB0_1470
